# attention: tiles 0-2 of the next unit prefetched by LDS-DMA under the current unit's epilogue (same batch/head), epilogue counted waits widened accordingly
# speedup vs baseline: 1.0024x; 1.0024x over previous
.LBB0_208:
	s_add_u32 s10, s90, 0x3c00000
	s_addc_u32 s11, s91, 0
	s_add_u32 s12, s90, 0xdc00000
	s_addc_u32 s13, s91, 0
	s_add_u32 s14, s90, 0x10000
	s_addc_u32 s15, s91, 0
	s_bfe_u32 s8, s57, 0x10006
	s_ashr_i32 s4, s57, 7
	v_lshrrev_b32_e32 v1, 5, v246
	s_ashr_i32 s37, s57, 8
	s_lshl_b32 s58, s4, 5
	s_lshl_b32 s9, s8, 6
	v_bfe_u32 v2, v222, 2, 2
	v_lshl_or_b32 v4, v1, 2, v2
	v_lshlrev_b32_e32 v2, 1, v246
	s_cmp_gt_u32 s56, 3
	v_and_b32_e32 v5, 32, v2
	v_lshlrev_b32_e32 v2, 3, v246
	s_cselect_b64 s[16:17], -1, 0
	s_cmp_lt_u32 s56, 4
	v_readlane_b32 s5, v254, 50
	v_and_b32_e32 v6, 24, v2
	v_lshlrev_b32_e32 v2, 3, v222
	s_cselect_b64 s[18:19], -1, 0
	s_lshl_b32 s21, s8, 10
	v_and_b32_e32 v3, 64, v240
	v_and_b32_e32 v148, 0x78, v2
	s_add_i32 s28, s5, s21
	v_xor_b32_e32 v2, 32, v240
	v_add_u32_e32 v3, 64, v3
	s_lshl_b32 s29, s4, 13
	s_and_b32 s4, 64, s57
	v_cmp_lt_i32_e32 vcc, v2, v3
	s_cmp_eq_u32 s8, 0
	s_cselect_b64 s[30:31], -1, 0
	v_cndmask_b32_e32 v2, v240, v2, vcc
	s_cmp_lg_u32 s4, 0
	s_sext_i32_i16 s4, s72
	v_lshl_add_u32 v149, v222, 2, s5
	v_ashrrev_i32_e32 v146, 4, v222
	v_lshlrev_b32_e32 v155, 2, v2
	s_cselect_b64 s[34:35], -1, 0
	s_cmp_gt_i32 s4, -1
	v_lshlrev_b32_e32 v2, 4, v246
	s_movk_i32 s4, 0x88
	v_and_b32_e32 v208, 0xf0, v2
	v_mad_u64_u32 v[2:3], s[4:5], v146, s4, v[148:149]
	v_mul_lo_u32 v3, v146, 24
	v_lshlrev_b32_e32 v157, 1, v2
	v_add_lshl_u32 v159, v2, v3, 1
	v_add_u32_e32 v2, 0x1100, v2
	s_cselect_b64 s[40:41], -1, 0
	v_lshlrev_b32_e32 v161, 1, v2
	v_add_u32_e32 v2, v3, v2
	s_movk_i32 s4, 0x140
	s_cmpk_lg_i32 s6, 0x100
	v_and_b32_e32 v144, 31, v222
	v_lshl_add_u32 v163, v2, 1, v241
	v_mad_u32_u24 v2, v4, s4, 0
	s_cselect_b64 s[48:49], -1, 0
	s_add_i32 s4, s29, 0
	v_lshlrev_b32_e32 v0, 3, v1
	v_lshlrev_b32_e32 v8, 8, v144
	s_add_i32 s4, s4, 0x18000
	v_add3_u32 v165, v2, v5, v6
	v_lshl_add_u32 v167, v246, 2, s4
	v_add3_u32 v169, s4, v8, v0
	v_add_u32_e32 v5, s4, v208
	s_lshl_b32 s4, s8, 7
	v_mul_u32_u24_e32 v7, 0x110, v144
	s_add_i32 s4, s4, 0
	v_lshlrev_b32_e32 v1, 4, v1
	v_add3_u32 v192, s4, v7, v1
	v_add_u32_e32 v193, s28, v1
	v_or_b32_e32 v1, s21, v1
	v_lshlrev_b32_e32 v2, 2, v144
	v_sub_u32_e32 v1, v1, v2
	s_and_b32 s4, s57, 0x80
	v_subrev_u32_e32 v1, s4, v1
	s_and_b32 s4, s57, 0xffffff00
	v_lshrrev_b32_e32 v154, 4, v246
	v_subrev_u32_e32 v1, s4, v1
	v_readlane_b32 s4, v254, 41
	v_ashrrev_i32_e32 v147, 31, v146
	v_or_b32_e32 v156, 4, v154
	v_or_b32_e32 v158, 8, v154
	v_or_b32_e32 v160, 12, v154
	v_or_b32_e32 v162, 16, v154
	v_or_b32_e32 v164, 20, v154
	v_or_b32_e32 v166, 24, v154
	v_or_b32_e32 v168, 28, v154
	s_add_u32 s4, s4, s54
	v_readlane_b32 s5, v254, 42
	v_add_u32_e32 v150, 64, v146
	v_lshlrev_b32_e32 v9, 8, v154
	v_lshlrev_b32_e32 v10, 8, v156
	v_lshlrev_b32_e32 v11, 8, v158
	v_lshlrev_b32_e32 v12, 8, v160
	v_lshlrev_b32_e32 v13, 8, v162
	v_lshlrev_b32_e32 v14, 8, v164
	v_lshlrev_b32_e32 v15, 8, v166
	v_lshlrev_b32_e32 v16, 8, v168
	v_and_or_b32 v4, s58, 32, v144
	v_lshlrev_b64 v[2:3], 11, v[146:147]
	s_addc_u32 s5, s5, s55
	v_ashrrev_i32_e32 v151, 31, v150
	v_lshl_add_u64 v[152:153], s[46:47], 0, v[208:209]
	v_add_u32_e32 v194, 0, v1
	v_lshl_add_u64 v[170:171], s[4:5], 0, v[2:3]
	s_lshl_b32 s59, s36, 6
	s_lshl_b32 s60, s6, 6
	s_add_i32 s61, s37, -1
	s_lshl_b32 s64, s9, 1
	v_lshlrev_b32_e32 v208, 1, v0
	v_lshlrev_b32_e32 v195, 2, v4
	v_add_u32_e32 v196, v5, v9
	v_add_u32_e32 v197, v5, v10
	v_add_u32_e32 v198, v5, v11
	v_add_u32_e32 v199, v5, v12
	v_add_u32_e32 v200, v5, v13
	v_add_u32_e32 v201, v5, v14
	v_add_u32_e32 v202, v5, v15
	v_add_u32_e32 v203, v5, v16
	s_mov_b32 s29, 0
	s_branch .LBB0_210

.LBB0_218:
	s_bfe_u32 s4, s36, 0x30004
	v_lshl_add_u32 v0, s4, 9, v222
	v_ashrrev_i32_e32 v1, 31, v0
	v_lshl_add_u64 v[0:1], v[0:1], 2, s[14:15]
	global_load_dword v232, v[0:1], off
	s_lshl_b32 s5, s36, 6
	s_and_b32 s66, s5, 0x2000
	s_lshl_b32 s5, s21, 7
	s_add_i32 s5, s5, s58
	s_ashr_i32 s8, s5, 31
	s_add_u32 s62, s5, s66
	s_addc_u32 s63, s8, 0
	v_mov_b32_e32 v1, s63
	s_lshl_b32 s89, s4, 7
	s_lshl_b32 s4, s4, 8
	s_mov_b32 s5, s67
	s_mov_b32 s65, s67
	v_lshl_add_u64 v[2:3], s[66:67], 0, v[146:147]
	v_lshlrev_b64 v[2:3], 10, v[2:3]
	v_mov_b32_e32 v5, v3
	v_add_u32_e32 v20, 0, v159
	s_cmp_eq_u32 s21, 0


	v_or_b32_e32 v0, s62, v144
	v_lshlrev_b64 v[0:1], 11, v[0:1]
	v_lshl_add_u64 v[0:1], s[46:47], 0, v[0:1]
	v_lshl_add_u64 v[0:1], v[0:1], 0, s[4:5]
	v_lshl_add_u64 v[0:1], v[0:1], 0, s[64:65]
	v_lshl_add_u64 v[0:1], v[0:1], 0, v[208:209]
	global_load_dwordx4 v[112:115], v[0:1], off
	global_load_dwordx4 v[116:119], v[0:1], off offset:32
	global_load_dwordx4 v[120:123], v[0:1], off offset:64
	global_load_dwordx4 v[124:127], v[0:1], off offset:96
	s_lshl_b32 s4, s66, 11
	s_lshl_b32 s5, s89, 1
	s_add_u32 s4, s4, s5
	s_add_u32 s80, s10, s4
	s_addc_u32 s81, s11, 0
	s_lshl_b32 s32, s56, 10
	v_lshlrev_b32_e32 v138, 4, v246
	v_mov_b32_e32 v142, 0xf0f0f1
	v_mov_b32_e32 v143, 0xcccccd
	s_movk_i32 s86, 0x110
	s_movk_i32 s87, 0x140
	s_mov_b32 s28, 0x9fe0000
	v_add_u32_e32 v139, s32, v138
	v_mul_hi_u32 v140, v139, v142
	v_mul_lo_u32 v141, v140, s86
	v_sub_u32_e32 v141, v139, v141
	v_cmp_gt_u32_e32 vcc, 0x100, v141
	s_nop 1
	v_cndmask_b32_e32 v141, 0, v141, vcc
	v_lshl_add_u32 v128, v140, 11, v141
	s_add_i32 s65, s32, 0x2000
	v_add_u32_e32 v139, s65, v138
	v_mul_hi_u32 v140, v139, v142
	v_mul_lo_u32 v141, v140, s86
	v_sub_u32_e32 v141, v139, v141
	v_cmp_gt_u32_e32 vcc, 0x100, v141
	s_nop 1
	v_cndmask_b32_e32 v141, 0, v141, vcc
	v_lshl_add_u32 v129, v140, 11, v141
	v_add_u32_e32 v139, s32, v138
	v_mul_hi_u32 v140, v139, v143
	v_mul_lo_u32 v141, v140, s87
	v_sub_u32_e32 v141, v139, v141
	v_cmp_gt_u32_e32 vcc, 0x100, v141
	s_nop 1
	v_cndmask_b32_e32 v141, 0, v141, vcc
	v_lshl_add_u32 v130, v140, 11, v141
	v_add_u32_e32 v130, s28, v130
	v_add_u32_e32 v139, s65, v138
	v_mul_hi_u32 v140, v139, v143
	v_mul_lo_u32 v141, v140, s87
	v_sub_u32_e32 v141, v139, v141
	v_cmp_gt_u32_e32 vcc, 0x100, v141
	s_nop 1
	v_cndmask_b32_e32 v141, 0, v141, vcc
	v_lshl_add_u32 v131, v140, 11, v141
	v_add_u32_e32 v131, s28, v131
	s_add_i32 s65, s32, 0x3c00
	s_cmp_eq_u32 s56, 0
	s_cselect_b32 s65, 0x4000, s65
	s_cselect_b32 s86, s86, s87
	s_mov_b32 s87, 0xcccccd
	s_cselect_b32 s87, 0xf0f0f1, s87
	s_cselect_b32 s28, 0, s28
	v_add_u32_e32 v139, s65, v138
	v_mul_hi_u32 v140, v139, s87
	v_mul_lo_u32 v141, v140, s86
	v_sub_u32_e32 v141, v139, v141
	v_cmp_gt_u32_e32 vcc, 0x100, v141
	s_nop 1
	v_cndmask_b32_e32 v141, 0, v141, vcc
	v_lshl_add_u32 v132, v140, 11, v141
	v_add_u32_e32 v132, s28, v132
	s_cmp_eq_u32 s29, 1
	s_cbranch_scc1 .Lpro_pf
	s_mov_b32 s28, 0
	s_add_i32 m0, s28, s32
	s_nop 0
	global_load_lds_dwordx4 v128, s[80:81]
	s_add_i32 m0, m0, 0x2000
	s_nop 0
	global_load_lds_dwordx4 v129, s[80:81]
	s_cmp_eq_u32 s56, 0
	s_cbranch_scc0 .Ldk_p0
	s_add_i32 m0, s28, 0x4000
	s_nop 0
	global_load_lds_dwordx4 v132, s[80:81]

.Lpw0:
	s_waitcnt vmcnt(0)
.Lpwd:
	s_branch .Lpro_join
.Lpro_pf:
	s_add_u32 s80, s80, 0x60000
	s_addc_u32 s81, s81, 0
	s_waitcnt vmcnt(0)

.LBB0_249:
	s_andn2_b64 vcc, exec, s[30:31]
	s_waitcnt lgkmcnt(0)
	s_barrier
	s_mov_b32 s29, 0
	s_add_i32 s4, s36, s6
	s_cmpk_gt_i32 s4, 0x3ff
	s_cbranch_scc1 .Lpf_none
	s_lshl_b32 s4, s36, 6
	s_and_b32 s4, s4, 0x2000
	s_lshl_b32 s4, s4, 11
	s_bfe_u32 s5, s36, 0x30004
	s_lshl_b32 s5, s5, 8
	s_add_u32 s4, s4, s5
	s_add_u32 s80, s10, s4
	s_addc_u32 s81, s11, 0
	s_mov_b32 s28, 0
	s_add_i32 m0, s28, s32
	s_nop 0
	global_load_lds_dwordx4 v128, s[80:81]
	s_add_i32 m0, m0, 0x2000
	s_nop 0
	global_load_lds_dwordx4 v129, s[80:81]
	s_cmp_eq_u32 s56, 0
	s_cbranch_scc0 .Ldk_q0
	s_add_i32 m0, s28, 0x4000
	s_nop 0
	global_load_lds_dwordx4 v132, s[80:81]

.Ldv_q1:
	s_mov_b32 s28, 0x20400
	s_add_i32 m0, s28, s32
	s_nop 0
	global_load_lds_dwordx4 v128, s[80:81]
	s_add_i32 m0, m0, 0x2000
	s_nop 0
	global_load_lds_dwordx4 v129, s[80:81]
	s_cmp_eq_u32 s56, 0
	s_cbranch_scc0 .Ldk_q2
	s_add_i32 m0, s28, 0x4000
	s_nop 0
	global_load_lds_dwordx4 v132, s[80:81]
.Ldk_q2:
	s_mov_b32 s29, 1
.Lpf_none:
	s_cbranch_vccnz .LBB0_252
	ds_read2st64_b32 v[66:67], v167 offset1:1
	ds_read2st64_b32 v[68:69], v167 offset0:2 offset1:3
	ds_read2st64_b32 v[70:71], v167 offset0:4 offset1:5
	ds_read2st64_b32 v[72:73], v167 offset0:6 offset1:7
	s_waitcnt lgkmcnt(3)
	v_lshlrev_b32_e32 v74, 16, v66
	v_and_b32_e32 v75, 0xffff0000, v66
	v_lshlrev_b32_e32 v76, 16, v67
	v_and_b32_e32 v77, 0xffff0000, v67
	ds_read2st64_b32 v[66:67], v167 offset0:8 offset1:9
	s_waitcnt lgkmcnt(3)
	v_lshlrev_b32_e32 v78, 16, v68
	v_and_b32_e32 v79, 0xffff0000, v68
	v_lshlrev_b32_e32 v96, 16, v69
	v_and_b32_e32 v97, 0xffff0000, v69
	ds_read2st64_b32 v[68:69], v167 offset0:10 offset1:11
	ds_read2st64_b32 v[102:103], v167 offset0:12 offset1:13
	ds_read2st64_b32 v[104:105], v167 offset0:14 offset1:15
	s_waitcnt lgkmcnt(3)
	v_lshlrev_b32_e32 v106, 16, v66
	v_and_b32_e32 v107, 0xffff0000, v66
	v_lshlrev_b32_e32 v108, 16, v67
	v_and_b32_e32 v109, 0xffff0000, v67
	ds_read2st64_b32 v[66:67], v167 offset0:16 offset1:17
	s_waitcnt lgkmcnt(3)
	v_lshlrev_b32_e32 v110, 16, v68
	v_and_b32_e32 v111, 0xffff0000, v68
	v_lshlrev_b32_e32 v112, 16, v69
	v_and_b32_e32 v113, 0xffff0000, v69
	ds_read2st64_b32 v[68:69], v167 offset0:18 offset1:19
	ds_read2st64_b32 v[118:119], v167 offset0:20 offset1:21
	ds_read2st64_b32 v[120:121], v167 offset0:22 offset1:23
	s_waitcnt lgkmcnt(3)
	v_lshlrev_b32_e32 v122, 16, v66
	v_and_b32_e32 v123, 0xffff0000, v66
	v_lshlrev_b32_e32 v124, 16, v67
	v_and_b32_e32 v125, 0xffff0000, v67
	ds_read2st64_b32 v[66:67], v167 offset0:24 offset1:25
	s_waitcnt lgkmcnt(3)
	v_lshlrev_b32_e32 v126, 16, v68
	v_and_b32_e32 v127, 0xffff0000, v68
	s_cmp_eq_u32 s29, 1
	s_cbranch_scc1 .Lev3
	s_waitcnt vmcnt(3)
.Lev3:
	s_waitcnt vmcnt(13)
	v_lshlrev_b32_e32 v128, 16, v69
	v_and_b32_e32 v129, 0xffff0000, v69
	ds_read2st64_b32 v[68:69], v167 offset0:26 offset1:27
	s_cmp_eq_u32 s29, 1
	s_cbranch_scc1 .Lev2
	s_waitcnt vmcnt(2)
.Lev2:
	s_waitcnt vmcnt(12)
	ds_read2st64_b32 v[134:135], v167 offset0:28 offset1:29
	s_cmp_eq_u32 s29, 1
	s_cbranch_scc1 .Lev1
	s_waitcnt vmcnt(1)
.Lev1:
	s_waitcnt vmcnt(11)
	ds_read2st64_b32 v[136:137], v167 offset0:30 offset1:31
	s_waitcnt lgkmcnt(3)
	v_lshlrev_b32_e32 v138, 16, v66
	v_and_b32_e32 v139, 0xffff0000, v66
	s_cmp_eq_u32 s29, 1
	s_cbranch_scc1 .Lev0
	s_waitcnt vmcnt(0)
.Lev0:
	s_waitcnt vmcnt(10)
	v_lshlrev_b32_e32 v140, 16, v67
	v_and_b32_e32 v141, 0xffff0000, v67
	v_mov_b32_e32 v66, v52
	v_mov_b32_e32 v67, v54
	v_mov_b32_e32 v54, v53
	s_waitcnt lgkmcnt(2)
	v_and_b32_e32 v53, 0xffff0000, v69
	v_and_b32_e32 v52, 0xffff0000, v68
	v_lshlrev_b32_e32 v143, 16, v69
	v_lshlrev_b32_e32 v142, 16, v68
	v_pk_fma_f32 v[68:69], v[54:55], v[64:65], v[52:53] op_sel_hi:[1,0,1]
	v_pk_fma_f32 v[66:67], v[66:67], v[64:65], v[142:143] op_sel_hi:[1,0,1]
	v_pk_mul_f32 v[52:53], v[68:69], v[68:69]
	s_waitcnt lgkmcnt(1)
	v_lshlrev_b32_e32 v55, 16, v135
	v_pk_fma_f32 v[142:143], v[66:67], v[66:67], v[52:53]
	v_mov_b32_e32 v52, v56
	v_mov_b32_e32 v53, v58
	v_lshlrev_b32_e32 v54, 16, v134
	v_pk_fma_f32 v[52:53], v[52:53], v[64:65], v[54:55] op_sel_hi:[1,0,1]
	v_mov_b32_e32 v58, v57
	v_and_b32_e32 v55, 0xffff0000, v135
	v_and_b32_e32 v54, 0xffff0000, v134
	v_pk_fma_f32 v[56:57], v[58:59], v[64:65], v[54:55] op_sel_hi:[1,0,1]
	s_waitcnt lgkmcnt(0)
	v_lshlrev_b32_e32 v59, 16, v137
	v_pk_mul_f32 v[54:55], v[56:57], v[56:57]
	v_lshlrev_b32_e32 v58, 16, v136
	v_pk_fma_f32 v[134:135], v[52:53], v[52:53], v[54:55]
	v_mov_b32_e32 v54, v60
	v_mov_b32_e32 v55, v62
	v_pk_fma_f32 v[54:55], v[54:55], v[64:65], v[58:59] op_sel_hi:[1,0,1]
	v_mov_b32_e32 v62, v61
	v_and_b32_e32 v59, 0xffff0000, v137
	v_and_b32_e32 v58, 0xffff0000, v136
	v_pk_fma_f32 v[34:35], v[34:35], v[64:65], v[76:77] op_sel_hi:[1,0,1]
	v_pk_fma_f32 v[32:33], v[32:33], v[64:65], v[74:75] op_sel_hi:[1,0,1]
	v_pk_fma_f32 v[58:59], v[62:63], v[64:65], v[58:59] op_sel_hi:[1,0,1]
	v_pk_mul_f32 v[62:63], v[34:35], v[34:35]
	v_pk_mul_f32 v[74:75], v[32:33], v[32:33]
	v_pk_fma_f32 v[36:37], v[36:37], v[64:65], v[78:79] op_sel_hi:[1,0,1]
	v_lshlrev_b32_e32 v98, 16, v70
	v_and_b32_e32 v99, 0xffff0000, v70
	v_pk_fma_f32 v[38:39], v[38:39], v[64:65], v[96:97] op_sel_hi:[1,0,1]
	v_pk_mul_f32 v[78:79], v[36:37], v[36:37]
	v_add_f32_e32 v62, v62, v63
	v_add_f32_e32 v63, v74, v75
	v_lshlrev_b32_e32 v70, 16, v71
	v_and_b32_e32 v71, 0xffff0000, v71
	v_pk_mul_f32 v[76:77], v[38:39], v[38:39]
	v_pk_fma_f32 v[40:41], v[40:41], v[64:65], v[98:99] op_sel_hi:[1,0,1]
	v_add_f32_e32 v62, v63, v62
	v_add_f32_e32 v63, v78, v79
	v_lshlrev_b32_e32 v100, 16, v72
	v_and_b32_e32 v101, 0xffff0000, v72
	v_pk_fma_f32 v[42:43], v[42:43], v[64:65], v[70:71] op_sel_hi:[1,0,1]
	v_pk_mul_f32 v[96:97], v[40:41], v[40:41]
	v_add_f32_e32 v62, v62, v63
	v_add_f32_e32 v63, v76, v77
	v_lshlrev_b32_e32 v72, 16, v73
	v_and_b32_e32 v73, 0xffff0000, v73
	v_pk_mul_f32 v[70:71], v[42:43], v[42:43]
	v_pk_fma_f32 v[44:45], v[44:45], v[64:65], v[100:101] op_sel_hi:[1,0,1]
	v_add_f32_e32 v62, v62, v63
	v_add_f32_e32 v63, v96, v97
	v_pk_fma_f32 v[46:47], v[46:47], v[64:65], v[72:73] op_sel_hi:[1,0,1]
	v_pk_mul_f32 v[98:99], v[44:45], v[44:45]
	v_add_f32_e32 v62, v62, v63
	v_add_f32_e32 v63, v70, v71
	v_pk_mul_f32 v[72:73], v[46:47], v[46:47]
	v_pk_fma_f32 v[16:17], v[16:17], v[64:65], v[106:107] op_sel_hi:[1,0,1]
	v_add_f32_e32 v62, v62, v63
	v_add_f32_e32 v63, v98, v99
	v_pk_fma_f32 v[18:19], v[18:19], v[64:65], v[108:109] op_sel_hi:[1,0,1]
	v_pk_mul_f32 v[106:107], v[16:17], v[16:17]
	v_add_f32_e32 v62, v62, v63
	v_add_f32_e32 v63, v72, v73
	v_pk_mul_f32 v[100:101], v[18:19], v[18:19]
	v_pk_fma_f32 v[20:21], v[20:21], v[64:65], v[110:111] op_sel_hi:[1,0,1]
	v_add_f32_e32 v62, v62, v63
	v_add_f32_e32 v63, v106, v107
	v_lshlrev_b32_e32 v114, 16, v102
	v_and_b32_e32 v115, 0xffff0000, v102
	v_pk_fma_f32 v[22:23], v[22:23], v[64:65], v[112:113] op_sel_hi:[1,0,1]
	v_pk_mul_f32 v[110:111], v[20:21], v[20:21]
	v_add_f32_e32 v62, v62, v63
	v_add_f32_e32 v63, v100, v101
	v_lshlrev_b32_e32 v102, 16, v103
	v_and_b32_e32 v103, 0xffff0000, v103
	v_pk_mul_f32 v[108:109], v[22:23], v[22:23]
	v_pk_fma_f32 v[24:25], v[24:25], v[64:65], v[114:115] op_sel_hi:[1,0,1]
	v_add_f32_e32 v62, v62, v63
	v_add_f32_e32 v63, v110, v111
	v_lshlrev_b32_e32 v116, 16, v104
	v_and_b32_e32 v117, 0xffff0000, v104
	v_pk_fma_f32 v[26:27], v[26:27], v[64:65], v[102:103] op_sel_hi:[1,0,1]
	v_pk_mul_f32 v[112:113], v[24:25], v[24:25]
	v_add_f32_e32 v62, v62, v63
	v_add_f32_e32 v63, v108, v109
	v_lshlrev_b32_e32 v104, 16, v105
	v_and_b32_e32 v105, 0xffff0000, v105
	v_pk_mul_f32 v[102:103], v[26:27], v[26:27]
	v_pk_fma_f32 v[28:29], v[28:29], v[64:65], v[116:117] op_sel_hi:[1,0,1]
	v_add_f32_e32 v62, v62, v63
	v_add_f32_e32 v63, v112, v113
	v_pk_fma_f32 v[30:31], v[30:31], v[64:65], v[104:105] op_sel_hi:[1,0,1]
	v_pk_mul_f32 v[114:115], v[28:29], v[28:29]
	v_add_f32_e32 v62, v62, v63
	v_add_f32_e32 v63, v102, v103
	v_pk_mul_f32 v[104:105], v[30:31], v[30:31]
	v_pk_fma_f32 v[0:1], v[0:1], v[64:65], v[122:123] op_sel_hi:[1,0,1]
	v_add_f32_e32 v62, v62, v63
	v_add_f32_e32 v63, v114, v115
	v_pk_fma_f32 v[2:3], v[2:3], v[64:65], v[124:125] op_sel_hi:[1,0,1]
	v_pk_mul_f32 v[122:123], v[0:1], v[0:1]
	v_add_f32_e32 v62, v62, v63
	v_add_f32_e32 v63, v104, v105
	v_pk_mul_f32 v[116:117], v[2:3], v[2:3]
	v_pk_fma_f32 v[4:5], v[4:5], v[64:65], v[126:127] op_sel_hi:[1,0,1]
	v_add_f32_e32 v62, v62, v63
	v_add_f32_e32 v63, v122, v123
	v_lshlrev_b32_e32 v130, 16, v118
	v_and_b32_e32 v131, 0xffff0000, v118
	v_pk_fma_f32 v[6:7], v[6:7], v[64:65], v[128:129] op_sel_hi:[1,0,1]
	v_pk_mul_f32 v[126:127], v[4:5], v[4:5]
	v_add_f32_e32 v62, v62, v63
	v_add_f32_e32 v63, v116, v117
	v_lshlrev_b32_e32 v118, 16, v119
	v_and_b32_e32 v119, 0xffff0000, v119
	v_lshlrev_b32_e32 v132, 16, v120
	v_and_b32_e32 v133, 0xffff0000, v120
	v_lshlrev_b32_e32 v120, 16, v121
	v_and_b32_e32 v121, 0xffff0000, v121
	v_pk_mul_f32 v[124:125], v[6:7], v[6:7]
	v_pk_fma_f32 v[8:9], v[8:9], v[64:65], v[130:131] op_sel_hi:[1,0,1]
	v_add_f32_e32 v62, v62, v63
	v_add_f32_e32 v63, v126, v127
	v_pk_fma_f32 v[10:11], v[10:11], v[64:65], v[118:119] op_sel_hi:[1,0,1]
	v_pk_mul_f32 v[128:129], v[8:9], v[8:9]
	v_pk_fma_f32 v[14:15], v[14:15], v[64:65], v[120:121] op_sel_hi:[1,0,1]
	v_pk_fma_f32 v[12:13], v[12:13], v[64:65], v[132:133] op_sel_hi:[1,0,1]
	v_add_f32_e32 v62, v62, v63
	v_add_f32_e32 v63, v124, v125
	v_pk_mul_f32 v[118:119], v[10:11], v[10:11]
	v_mov_b32_e32 v130, v13
	v_mov_b32_e32 v131, v15
	v_add_f32_e32 v62, v62, v63
	v_add_f32_e32 v63, v128, v129
	v_mov_b32_e32 v120, v12
	v_mov_b32_e32 v121, v14
	v_pk_mul_f32 v[130:131], v[130:131], v[130:131]
	v_pk_fma_f32 v[50:51], v[50:51], v[64:65], v[140:141] op_sel_hi:[1,0,1]
	v_pk_fma_f32 v[48:49], v[48:49], v[64:65], v[138:139] op_sel_hi:[1,0,1]
	v_add_f32_e32 v62, v62, v63
	v_add_f32_e32 v63, v118, v119
	v_pk_fma_f32 v[120:121], v[120:121], v[120:121], v[130:131]
	v_mov_b32_e32 v130, v49
	v_mov_b32_e32 v131, v51
	v_add_f32_e32 v62, v62, v63
	v_mov_b32_e32 v64, v48
	v_mov_b32_e32 v65, v50
	v_pk_mul_f32 v[130:131], v[130:131], v[130:131]
	v_add_f32_e32 v62, v62, v120
	v_pk_fma_f32 v[64:65], v[64:65], v[64:65], v[130:131]
	v_add_f32_e32 v62, v62, v121
	v_add_f32_e32 v62, v62, v64
	v_add_f32_e32 v62, v62, v65
	v_add_f32_e32 v62, v62, v142
	v_add_f32_e32 v62, v62, v143
	v_pk_mul_f32 v[60:61], v[58:59], v[58:59]
	v_add_f32_e32 v62, v62, v134
	v_pk_fma_f32 v[60:61], v[54:55], v[54:55], v[60:61]
	v_add_f32_e32 v62, v62, v135
	v_add_f32_e32 v60, v62, v60
	v_add_f32_e32 v60, v60, v61
	ds_bpermute_b32 v61, v155, v60
	s_waitcnt lgkmcnt(0)
	v_add_f32_e32 v60, v60, v61
	v_fmamk_f32 v60, v60, 0x3c000000, v236
	v_mul_f32_e32 v61, 0x4b800000, v60
	v_cmp_gt_f32_e32 vcc, s3, v60
	s_nop 1
	v_cndmask_b32_e32 v60, v60, v61, vcc
	v_rsq_f32_e32 v60, v60
	s_nop 0
	v_mul_f32_e32 v61, 0x45800000, v60
	v_cndmask_b32_e32 v60, v60, v61, vcc
	v_pk_mul_f32 v[0:1], v[0:1], v[60:61] op_sel_hi:[1,0]
	v_pk_mul_f32 v[2:3], v[2:3], v[60:61] op_sel_hi:[1,0]
	v_cvt_pk_bf16_f32 v0, v0, v1
	v_cvt_pk_bf16_f32 v1, v2, v3
	v_pk_mul_f32 v[2:3], v[4:5], v[60:61] op_sel_hi:[1,0]
	v_pk_mul_f32 v[4:5], v[6:7], v[60:61] op_sel_hi:[1,0]
	v_cvt_pk_bf16_f32 v2, v2, v3
	v_cvt_pk_bf16_f32 v3, v4, v5
	ds_write2_b64 v169, v[0:1], v[2:3] offset0:16 offset1:18
	v_pk_mul_f32 v[0:1], v[8:9], v[60:61] op_sel_hi:[1,0]
	v_pk_mul_f32 v[2:3], v[10:11], v[60:61] op_sel_hi:[1,0]
	v_cvt_pk_bf16_f32 v0, v0, v1
	v_cvt_pk_bf16_f32 v1, v2, v3
	v_pk_mul_f32 v[2:3], v[12:13], v[60:61] op_sel_hi:[1,0]
	v_pk_mul_f32 v[4:5], v[14:15], v[60:61] op_sel_hi:[1,0]
	v_cvt_pk_bf16_f32 v2, v2, v3
	v_cvt_pk_bf16_f32 v3, v4, v5
	ds_write2_b64 v169, v[0:1], v[2:3] offset0:20 offset1:22
	v_pk_mul_f32 v[0:1], v[48:49], v[60:61] op_sel_hi:[1,0]
	v_pk_mul_f32 v[2:3], v[50:51], v[60:61] op_sel_hi:[1,0]
	v_cvt_pk_bf16_f32 v0, v0, v1
	v_cvt_pk_bf16_f32 v1, v2, v3
	v_mov_b32_e32 v2, v66
	v_mov_b32_e32 v3, v68
	v_mov_b32_e32 v68, v67
	v_pk_mul_f32 v[2:3], v[2:3], v[60:61] op_sel_hi:[1,0]
	v_pk_mul_f32 v[4:5], v[68:69], v[60:61] op_sel_hi:[1,0]
	v_pk_mul_f32 v[32:33], v[32:33], v[60:61] op_sel_hi:[1,0]
	v_pk_mul_f32 v[34:35], v[34:35], v[60:61] op_sel_hi:[1,0]
	v_pk_mul_f32 v[16:17], v[16:17], v[60:61] op_sel_hi:[1,0]
	v_pk_mul_f32 v[18:19], v[18:19], v[60:61] op_sel_hi:[1,0]
	v_cvt_pk_bf16_f32 v2, v2, v3
	v_cvt_pk_bf16_f32 v3, v4, v5
	v_cvt_pk_bf16_f32 v32, v32, v33
	v_cvt_pk_bf16_f32 v33, v34, v35
	v_pk_mul_f32 v[34:35], v[36:37], v[60:61] op_sel_hi:[1,0]
	v_pk_mul_f32 v[36:37], v[38:39], v[60:61] op_sel_hi:[1,0]
	v_cvt_pk_bf16_f32 v16, v16, v17
	v_cvt_pk_bf16_f32 v17, v18, v19
	v_pk_mul_f32 v[18:19], v[20:21], v[60:61] op_sel_hi:[1,0]
	v_pk_mul_f32 v[20:21], v[22:23], v[60:61] op_sel_hi:[1,0]
	ds_write2_b64 v169, v[0:1], v[2:3] offset0:24 offset1:26
	v_mov_b32_e32 v0, v52
	v_mov_b32_e32 v1, v56
	v_mov_b32_e32 v56, v53
	v_cvt_pk_bf16_f32 v34, v34, v35
	v_cvt_pk_bf16_f32 v35, v36, v37
	v_cvt_pk_bf16_f32 v18, v18, v19
	v_cvt_pk_bf16_f32 v19, v20, v21
	v_pk_mul_f32 v[0:1], v[0:1], v[60:61] op_sel_hi:[1,0]
	v_pk_mul_f32 v[2:3], v[56:57], v[60:61] op_sel_hi:[1,0]
	ds_write2_b64 v169, v[32:33], v[34:35] offset1:2
	v_pk_mul_f32 v[32:33], v[40:41], v[60:61] op_sel_hi:[1,0]
	v_pk_mul_f32 v[34:35], v[42:43], v[60:61] op_sel_hi:[1,0]
	ds_write2_b64 v169, v[16:17], v[18:19] offset0:8 offset1:10
	v_pk_mul_f32 v[16:17], v[24:25], v[60:61] op_sel_hi:[1,0]
	v_pk_mul_f32 v[18:19], v[26:27], v[60:61] op_sel_hi:[1,0]
	v_cvt_pk_bf16_f32 v0, v0, v1
	v_cvt_pk_bf16_f32 v1, v2, v3
	v_mov_b32_e32 v2, v54
	v_mov_b32_e32 v3, v58
	v_mov_b32_e32 v58, v55
	v_cvt_pk_bf16_f32 v32, v32, v33
	v_cvt_pk_bf16_f32 v33, v34, v35
	v_pk_mul_f32 v[34:35], v[44:45], v[60:61] op_sel_hi:[1,0]
	v_pk_mul_f32 v[36:37], v[46:47], v[60:61] op_sel_hi:[1,0]
	v_cvt_pk_bf16_f32 v16, v16, v17
	v_cvt_pk_bf16_f32 v17, v18, v19
	v_pk_mul_f32 v[18:19], v[28:29], v[60:61] op_sel_hi:[1,0]
	v_pk_mul_f32 v[20:21], v[30:31], v[60:61] op_sel_hi:[1,0]
	v_pk_mul_f32 v[2:3], v[2:3], v[60:61] op_sel_hi:[1,0]
	v_pk_mul_f32 v[4:5], v[58:59], v[60:61] op_sel_hi:[1,0]
	v_cvt_pk_bf16_f32 v34, v34, v35
	v_cvt_pk_bf16_f32 v35, v36, v37
	v_cvt_pk_bf16_f32 v18, v18, v19
	v_cvt_pk_bf16_f32 v19, v20, v21
	v_cvt_pk_bf16_f32 v2, v2, v3
	v_cvt_pk_bf16_f32 v3, v4, v5
	ds_write2_b64 v169, v[32:33], v[34:35] offset0:4 offset1:6
	ds_write2_b64 v169, v[16:17], v[18:19] offset0:12 offset1:14
	ds_write2_b64 v169, v[0:1], v[2:3] offset0:28 offset1:30
	s_waitcnt lgkmcnt(0)
	s_andn2_b64 vcc, exec, s[40:41]
	s_cbranch_vccnz .LBB0_252
	ds_read_b128 v[0:3], v196
	s_lshl_b32 s66, s89, 1
	v_mov_b32_e32 v7, s63
	v_or_b32_e32 v6, s62, v154
	v_lshl_add_u64 v[4:5], v[152:153], 0, s[66:67]
	v_lshlrev_b64 v[6:7], 11, v[6:7]
	v_lshl_add_u64 v[6:7], v[4:5], 0, v[6:7]
	s_waitcnt lgkmcnt(0)
	global_store_dwordx4 v[6:7], v[0:3], off
	ds_read_b128 v[0:3], v197
	v_mov_b32_e32 v7, s63
	v_or_b32_e32 v6, s62, v156
	v_lshlrev_b64 v[6:7], 11, v[6:7]
	v_lshl_add_u64 v[6:7], v[4:5], 0, v[6:7]
	s_waitcnt lgkmcnt(0)
	global_store_dwordx4 v[6:7], v[0:3], off
	ds_read_b128 v[0:3], v198
	v_mov_b32_e32 v7, s63
	v_or_b32_e32 v6, s62, v158
	v_lshlrev_b64 v[6:7], 11, v[6:7]
	v_lshl_add_u64 v[6:7], v[4:5], 0, v[6:7]
	s_waitcnt lgkmcnt(0)
	global_store_dwordx4 v[6:7], v[0:3], off
	ds_read_b128 v[0:3], v199
	v_mov_b32_e32 v7, s63
	v_or_b32_e32 v6, s62, v160
	v_lshlrev_b64 v[6:7], 11, v[6:7]
	v_lshl_add_u64 v[6:7], v[4:5], 0, v[6:7]
	s_waitcnt lgkmcnt(0)
	global_store_dwordx4 v[6:7], v[0:3], off
	ds_read_b128 v[0:3], v200
	v_mov_b32_e32 v7, s63
	v_or_b32_e32 v6, s62, v162
	v_lshlrev_b64 v[6:7], 11, v[6:7]
	v_lshl_add_u64 v[6:7], v[4:5], 0, v[6:7]
	s_waitcnt lgkmcnt(0)
	global_store_dwordx4 v[6:7], v[0:3], off
	ds_read_b128 v[0:3], v201
	v_mov_b32_e32 v7, s63
	v_or_b32_e32 v6, s62, v164
	v_lshlrev_b64 v[6:7], 11, v[6:7]
	v_lshl_add_u64 v[6:7], v[4:5], 0, v[6:7]
	s_waitcnt lgkmcnt(0)
	global_store_dwordx4 v[6:7], v[0:3], off
	ds_read_b128 v[0:3], v202
	v_mov_b32_e32 v7, s63
	v_or_b32_e32 v6, s62, v166
	v_lshlrev_b64 v[6:7], 11, v[6:7]
	v_lshl_add_u64 v[6:7], v[4:5], 0, v[6:7]
	s_waitcnt lgkmcnt(0)
	global_store_dwordx4 v[6:7], v[0:3], off
	ds_read_b128 v[0:3], v203
	v_mov_b32_e32 v7, s63
	v_or_b32_e32 v6, s62, v168
	v_lshlrev_b64 v[6:7], 11, v[6:7]
	v_lshl_add_u64 v[4:5], v[4:5], 0, v[6:7]
	s_waitcnt lgkmcnt(0)
	global_store_dwordx4 v[4:5], v[0:3], off
